# same as previous plus one wait state ahead of the first VALU read of the QK p0 accumulator (MFMA result hazard distance)
# baseline (speedup 1.0000x reference)
.LBB0_325:
	s_waitcnt lgkmcnt(4)
	v_mfma_f32_32x32x16_bf16 v[96:111], v[80:83], v[144:147], v[64:79]
	v_mov_b32_e32 v170, v148
	s_add_i32 s0, s74, s97
	s_sub_i32 s0, s0, 63
	v_mfma_f32_32x32x16_bf16 v[96:111], v[202:205], v[140:143], v[96:111]
	v_cvt_f32_i32_e32 v148, s0
	v_mov_b32_e32 v174, v152
	v_mov_b32_e32 v175, v153
	v_mfma_f32_32x32x16_bf16 v[96:111], v[194:197], v[136:139], v[96:111]
	v_fma_f32 v254, v208, v148, -v207
	v_mov_b32_e32 v176, v154
	v_mov_b32_e32 v177, v155
	v_mfma_f32_32x32x16_bf16 v[96:111], v[186:189], v[132:135], v[96:111]
	v_add_f32_e32 v255, v237, v254
	v_mov_b32_e32 v168, v162
	v_mov_b32_e32 v162, v156
	v_mfma_f32_32x32x16_bf16 v[80:95], v[198:201], v[144:147], v[64:79]
	v_mov_b32_e32 v163, v157
	v_mov_b32_e32 v166, v160
	v_mov_b32_e32 v167, v161
	v_mov_b32_e32 v171, v149
	v_mov_b32_e32 v172, v150
	v_mov_b32_e32 v173, v151
	v_mfma_f32_32x32x16_bf16 v[80:95], v[190:193], v[140:143], v[80:95]
	s_nop 0
	v_add_f32_e32 v96, v254, v96
	v_exp_f32_e32 v96, v96
	v_add_f32_e32 v97, v254, v97
	v_exp_f32_e32 v97, v97
	v_add_f32_e32 v98, v254, v98
	v_exp_f32_e32 v98, v98
	v_add_f32_e32 v99, v254, v99
	v_exp_f32_e32 v99, v99
	v_add_f32_e32 v100, v254, v100
	v_exp_f32_e32 v100, v100
	v_mfma_f32_32x32x16_bf16 v[80:95], v[246:249], v[136:139], v[80:95]
	v_add_f32_e32 v101, v254, v101
	v_exp_f32_e32 v101, v101
	v_add_f32_e32 v102, v254, v102
	v_exp_f32_e32 v102, v102
	v_add_f32_e32 v103, v254, v103
	v_exp_f32_e32 v103, v103
	v_add_f32_e32 v104, v254, v104
	v_exp_f32_e32 v104, v104
	v_add_f32_e32 v105, v254, v105
	v_exp_f32_e32 v105, v105
	v_mfma_f32_32x32x16_bf16 v[80:95], v[250:253], v[132:135], v[80:95]
	v_add_f32_e32 v106, v254, v106
	v_exp_f32_e32 v106, v106
	v_add_f32_e32 v107, v254, v107
	v_exp_f32_e32 v107, v107
	v_add_f32_e32 v108, v254, v108
	v_exp_f32_e32 v108, v108
	v_add_f32_e32 v109, v254, v109
	v_exp_f32_e32 v109, v109
	v_add_f32_e32 v110, v254, v110
	v_exp_f32_e32 v110, v110
	v_add_f32_e32 v111, v254, v111
	v_exp_f32_e32 v111, v111
	s_cmp_le_i32 s97, s78
	s_cbranch_scc1 .LBB0_327
	v_cmp_gt_i32_e64 s[60:61], 26, v240
	v_cmp_gt_i32_e64 s[62:63], 27, v240
	v_cmp_gt_i32_e64 s[58:59], 25, v240
	s_and_b64 s[60:61], s[62:63], s[60:61]
	v_cmp_gt_i32_e64 s[56:57], 24, v240
	s_and_b64 s[58:59], s[60:61], s[58:59]
	v_cmp_gt_i32_e64 s[54:55], 19, v240
	s_and_b64 s[56:57], s[58:59], s[56:57]
	v_cmp_gt_i32_e64 s[52:53], 18, v240
	s_and_b64 s[54:55], s[56:57], s[54:55]
	v_cmp_gt_i32_e64 s[50:51], 17, v240
	s_and_b64 s[52:53], s[54:55], s[52:53]
	v_cmp_gt_i32_e64 s[48:49], 16, v240
	s_and_b64 s[50:51], s[52:53], s[50:51]
	v_cmp_gt_i32_e64 s[46:47], 11, v240
	s_and_b64 s[48:49], s[50:51], s[48:49]
	v_cmp_gt_i32_e64 s[44:45], 10, v240
	s_and_b64 s[46:47], s[48:49], s[46:47]
	v_cmp_gt_i32_e64 s[42:43], 9, v240
	s_and_b64 s[44:45], s[46:47], s[44:45]
	v_cmp_gt_i32_e64 s[40:41], 8, v240
	s_and_b64 s[42:43], s[44:45], s[42:43]
	v_cmp_gt_i32_e64 s[38:39], 3, v240
	s_and_b64 s[40:41], s[42:43], s[40:41]
	v_cmp_gt_i32_e64 s[36:37], 2, v240
	s_and_b64 s[38:39], s[40:41], s[38:39]
	v_cmp_gt_i32_e64 s[34:35], 1, v240
	s_and_b64 s[36:37], s[38:39], s[36:37]
	v_cmp_gt_i32_e64 s[30:31], 0, v240
	s_and_b64 s[34:35], s[36:37], s[34:35]
	s_and_b64 s[30:31], s[34:35], s[30:31]
	v_cmp_gt_i32_e64 s[28:29], 58, v240
	v_cndmask_b32_e64 v96, v96, v113, s[30:31]
	v_cmp_gt_i32_e64 s[30:31], 59, v240
	v_cmp_gt_i32_e64 s[26:27], 57, v240
	s_and_b64 s[28:29], s[30:31], s[28:29]
	v_cmp_gt_i32_e64 s[24:25], 56, v240
	s_and_b64 s[26:27], s[28:29], s[26:27]
	v_cmp_gt_i32_e64 s[22:23], 51, v240
	s_and_b64 s[24:25], s[26:27], s[24:25]
	v_cmp_gt_i32_e64 s[20:21], 50, v240
	s_and_b64 s[22:23], s[24:25], s[22:23]
	v_cmp_gt_i32_e64 s[18:19], 49, v240
	s_and_b64 s[20:21], s[22:23], s[20:21]
	v_cmp_gt_i32_e64 s[16:17], 48, v240
	s_and_b64 s[18:19], s[20:21], s[18:19]
	v_cmp_gt_i32_e64 s[14:15], 43, v240
	s_and_b64 s[16:17], s[18:19], s[16:17]
	v_cmp_gt_i32_e64 s[12:13], 42, v240
	s_and_b64 s[14:15], s[16:17], s[14:15]
	v_cmp_gt_i32_e64 s[10:11], 41, v240
	s_and_b64 s[12:13], s[14:15], s[12:13]
	v_cmp_gt_i32_e64 s[8:9], 40, v240
	s_and_b64 s[10:11], s[12:13], s[10:11]
	v_cmp_gt_i32_e64 s[6:7], 35, v240
	s_and_b64 s[8:9], s[10:11], s[8:9]
	v_cmp_gt_i32_e64 s[4:5], 34, v240
	s_and_b64 s[6:7], s[8:9], s[6:7]
	v_cmp_gt_i32_e64 s[0:1], 33, v240
	s_and_b64 s[4:5], s[6:7], s[4:5]
	v_cmp_gt_i32_e32 vcc, 32, v240
	s_and_b64 s[0:1], s[4:5], s[0:1]
	s_and_b64 vcc, s[0:1], vcc
	v_cndmask_b32_e64 v111, v111, v113, s[62:63]
	v_cndmask_b32_e64 v110, v110, v113, s[60:61]
	v_cndmask_b32_e64 v109, v109, v113, s[58:59]
	v_cndmask_b32_e64 v108, v108, v113, s[56:57]
	v_cndmask_b32_e64 v107, v107, v113, s[54:55]
	v_cndmask_b32_e64 v106, v106, v113, s[52:53]
	v_cndmask_b32_e64 v105, v105, v113, s[50:51]
	v_cndmask_b32_e64 v104, v104, v113, s[48:49]
	v_cndmask_b32_e64 v103, v103, v113, s[46:47]
	v_cndmask_b32_e64 v102, v102, v113, s[44:45]
	v_cndmask_b32_e64 v101, v101, v113, s[42:43]
	v_cndmask_b32_e64 v100, v100, v113, s[40:41]
	v_cndmask_b32_e64 v99, v99, v113, s[38:39]
	v_cndmask_b32_e64 v98, v98, v113, s[36:37]
	v_cndmask_b32_e64 v97, v97, v113, s[34:35]
	v_cndmask_b32_e64 v95, v95, v228, s[30:31]
	v_cndmask_b32_e64 v94, v94, v228, s[28:29]
	v_cndmask_b32_e64 v93, v93, v228, s[26:27]
	v_cndmask_b32_e64 v92, v92, v228, s[24:25]
	v_cndmask_b32_e64 v91, v91, v228, s[22:23]
	v_cndmask_b32_e64 v90, v90, v228, s[20:21]
	v_cndmask_b32_e64 v89, v89, v228, s[18:19]
	v_cndmask_b32_e64 v88, v88, v228, s[16:17]
	v_cndmask_b32_e64 v87, v87, v228, s[14:15]
	v_cndmask_b32_e64 v86, v86, v228, s[12:13]
	v_cndmask_b32_e64 v85, v85, v228, s[10:11]
	v_cndmask_b32_e64 v84, v84, v228, s[8:9]
	v_cndmask_b32_e64 v83, v83, v228, s[6:7]
	v_cndmask_b32_e64 v82, v82, v228, s[4:5]
	v_cndmask_b32_e64 v81, v81, v228, s[0:1]
	v_cndmask_b32_e32 v80, v80, v228, vcc
